# preprocessing jobs rotated (tiles 32..65 first, then 0..31 in unit order) with per-row-tile w_in dependency; 128 stolen units
# baseline (speedup 1.0000x reference)
.LBB0_799:
	s_waitcnt vmcnt(4)
	s_add_i32 s43, s43, 128
	s_add_i32 s100, s43, 0xfffffef8
	s_cmp_ge_u32 s43, 0x288
	s_cselect_b32 s43, s100, s43
	s_add_i32 s100, s43, 0xfffffe80
	s_lshr_b32 s100, s100, 2
	s_cmp_lt_u32 s100, 32
	s_cselect_b32 s101, 6, 2
	s_cmp_lt_u32 s100, 64
	s_cselect_b32 s101, s101, 0
	s_cmp_eq_u32 s101, 0
	s_cbranch_scc1 .Lpw_done
	s_mul_i32 s100, s100, 48
	s_addk_i32 s100, 0x1000
	s_mov_b32 vcc_lo, 0
